# P1/P7 staged-epilogue copy-out rewritten: batched LDS reads, strength-reduced addressing (on top of v26)
# speedup vs baseline: 1.0073x; 1.0002x over previous
; DI unsigned pack2(float a, float b) { f2_t v = {a, b}; bf2_t r = __builtin_convertvector(v, bf2_t); return __builtin_bit_cast(unsigned, r); }
; DI float sigmoidf_(float x) { return frcp(1.f + fexp2(-1.44269504089f * x)); }
; DI float siluf_(float x) { return x * sigmoidf_(x); }
; template <class Epi>
; DI void apply_epi_staged(WVP char* smem, AccT& acc, int bc0, const Epi& epi) {
;     ...
;   for (int bj = 0; bj < 2; ++bj) for (int m = 0; m < 4; ++m) {
;     for (int n = 0; n < 2; ++n) {
;       const int rl = wr2 * 64 + m * 16 + fq2 * 4, tc = bj * HALF + wc2 * 32 + n * 16 + fr2;
;       f32x4 r0, r1;
;       epi.tr(acc[0][bj][m][n], acc[1][bj][m][n], rl, bc0 + tc, bj * 8 + m * 2 + n, t2, r0, r1);
;       uint2 v0; v0.x = pack2(r0[0], r0[1]); v0.y = pack2(r0[2], r0[3]);
;       *(uint2*)(smem + tc * PITCH + rl * 2) = v0;
;       if (NC == 256) { uint2 v1; v1.x = pack2(r1[0], r1[1]); v1.y = pack2(r1[2], r1[3]); *(uint2*)(smem + tc * PITCH + (HALF + rl) * 2) = v1; }
;   DI void tr(const f32x4& a0, const f32x4& a1, int, int, int, int, f32x4& r0, f32x4& r1) const {
;     for (int j = 0; j < 4; ++j) r0[j] = ACT == 0 ? siluf_(a0[j]) * a1[j] : a0[j] * sigmoidf_(a1[j]);
;     r1 = r0; }
.LBB0_164:
	v_mbcnt_lo_u32_b32 v130, -1, 0
	v_mbcnt_hi_u32_b32 v130, -1, v130
	v_mul_f32_e32 v131, 0xbfb8aa3b, v123
	v_add_u32_e32 v0, s3, v130
	v_exp_f32_e32 v131, v131
	v_readfirstlane_b32 s0, v0
	s_ashr_i32 s0, s0, 1
	s_and_b32 s1, s0, 0x60
	v_and_or_b32 v132, v130, 15, s1
	v_lshrrev_b32_e32 v130, 1, v130
	v_and_b32_e32 v133, 24, v130
	v_mul_f32_e32 v130, 0xbfb8aa3b, v122
	v_exp_f32_e32 v130, v130
	v_add_f32_e32 v131, 1.0, v131
	v_rcp_f32_e32 v131, v131
	s_and_b32 s0, s0, 0xffffff80
	v_add_f32_e32 v130, 1.0, v130
	v_rcp_f32_e32 v130, v130
	s_add_i32 s0, s0, 0
	v_pk_mul_f32 v[122:123], v[122:123], v[130:131]
	s_nop 0
	v_pk_mul_f32 v[122:123], v[122:123], v[126:127]
	v_mul_f32_e32 v126, 0xbfb8aa3b, v124
	v_mul_f32_e32 v127, 0xbfb8aa3b, v125
	v_exp_f32_e32 v126, v126
	v_exp_f32_e32 v127, v127
	v_add_f32_e32 v126, 1.0, v126
	v_add_f32_e32 v127, 1.0, v127
	v_rcp_f32_e32 v126, v126
	v_rcp_f32_e32 v127, v127
	s_nop 0
	v_pk_mul_f32 v[124:125], v[124:125], v[126:127]
	v_cvt_pk_bf16_f32 v126, v122, v123
	v_mul_f32_e32 v123, 0xbfb8aa3b, v114
	v_exp_f32_e32 v123, v123
	v_pk_mul_f32 v[124:125], v[124:125], v[128:129]
	v_mul_u32_u24_e32 v122, 0x110, v132
	v_cvt_pk_bf16_f32 v127, v124, v125
	v_add_f32_e32 v123, 1.0, v123
	v_rcp_f32_e32 v124, v123
	v_mul_f32_e32 v123, 0xbfb8aa3b, v115
	v_exp_f32_e32 v123, v123
	v_add3_u32 v122, s0, v133, v122
	v_add_f32_e32 v123, 1.0, v123
	v_rcp_f32_e32 v125, v123
	s_nop 0
	v_pk_mul_f32 v[114:115], v[114:115], v[124:125]
	s_nop 0
	v_pk_mul_f32 v[114:115], v[114:115], v[118:119]
	v_mul_f32_e32 v118, 0xbfb8aa3b, v116
	v_mul_f32_e32 v119, 0xbfb8aa3b, v117
	v_exp_f32_e32 v118, v118
	v_exp_f32_e32 v119, v119
	v_cvt_pk_bf16_f32 v114, v114, v115
	v_add_f32_e32 v118, 1.0, v118
	v_add_f32_e32 v119, 1.0, v119
	v_rcp_f32_e32 v118, v118
	v_rcp_f32_e32 v119, v119
	s_nop 0
	v_pk_mul_f32 v[116:117], v[116:117], v[118:119]
	s_nop 0
	v_pk_mul_f32 v[116:117], v[116:117], v[120:121]
	s_nop 0
	v_cvt_pk_bf16_f32 v115, v116, v117
	v_mul_f32_e32 v116, 0xbfb8aa3b, v106
	v_mul_f32_e32 v117, 0xbfb8aa3b, v107
	v_exp_f32_e32 v116, v116
	v_exp_f32_e32 v117, v117
	v_add_f32_e32 v116, 1.0, v116
	v_add_f32_e32 v117, 1.0, v117
	v_rcp_f32_e32 v116, v116
	v_rcp_f32_e32 v117, v117
	s_nop 0
	v_pk_mul_f32 v[106:107], v[106:107], v[116:117]
	s_nop 0
	v_pk_mul_f32 v[106:107], v[106:107], v[110:111]
	v_mul_f32_e32 v110, 0xbfb8aa3b, v108
	v_mul_f32_e32 v111, 0xbfb8aa3b, v109
	v_exp_f32_e32 v110, v110
	v_exp_f32_e32 v111, v111
	v_cvt_pk_bf16_f32 v106, v106, v107
	v_add_f32_e32 v110, 1.0, v110
	v_add_f32_e32 v111, 1.0, v111
	v_rcp_f32_e32 v110, v110
	v_rcp_f32_e32 v111, v111
	s_nop 0
	v_pk_mul_f32 v[108:109], v[108:109], v[110:111]
	s_nop 0
	v_pk_mul_f32 v[108:109], v[108:109], v[112:113]
	s_nop 0
	v_cvt_pk_bf16_f32 v107, v108, v109
	ds_write2_b64 v122, v[126:127], v[106:107] offset1:4
	v_mul_f32_e32 v106, 0xbfb8aa3b, v98
	v_mul_f32_e32 v107, 0xbfb8aa3b, v99
	v_exp_f32_e32 v106, v106
	v_exp_f32_e32 v107, v107
	v_add_f32_e32 v106, 1.0, v106
	v_add_f32_e32 v107, 1.0, v107
	v_rcp_f32_e32 v106, v106
	v_rcp_f32_e32 v107, v107
	s_nop 0
	v_pk_mul_f32 v[98:99], v[98:99], v[106:107]
	s_nop 0
	v_pk_mul_f32 v[98:99], v[98:99], v[102:103]
	v_mul_f32_e32 v102, 0xbfb8aa3b, v100
	v_mul_f32_e32 v103, 0xbfb8aa3b, v101
	v_exp_f32_e32 v102, v102
	v_exp_f32_e32 v103, v103
	v_cvt_pk_bf16_f32 v98, v98, v99
	v_add_f32_e32 v102, 1.0, v102
	v_add_f32_e32 v103, 1.0, v103
	v_rcp_f32_e32 v102, v102
	v_rcp_f32_e32 v103, v103
	s_nop 0
	v_pk_mul_f32 v[100:101], v[100:101], v[102:103]
	s_nop 0
	v_pk_mul_f32 v[100:101], v[100:101], v[104:105]
	s_nop 0
	v_cvt_pk_bf16_f32 v99, v100, v101
	v_add_u32_e32 v100, 0x1000, v122
	ds_write2_b64 v100, v[114:115], v[98:99] offset0:32 offset1:36
	v_mul_f32_e32 v98, 0xbfb8aa3b, v90
	v_mul_f32_e32 v99, 0xbfb8aa3b, v91
	v_exp_f32_e32 v98, v98
	v_exp_f32_e32 v99, v99
	v_add_f32_e32 v98, 1.0, v98
	v_add_f32_e32 v99, 1.0, v99
	v_rcp_f32_e32 v98, v98
	v_rcp_f32_e32 v99, v99
	s_nop 0
	v_pk_mul_f32 v[90:91], v[90:91], v[98:99]
	s_nop 0
	v_pk_mul_f32 v[90:91], v[90:91], v[94:95]
	v_mul_f32_e32 v94, 0xbfb8aa3b, v92
	v_mul_f32_e32 v95, 0xbfb8aa3b, v93
	v_exp_f32_e32 v94, v94
	v_exp_f32_e32 v95, v95
	v_cvt_pk_bf16_f32 v90, v90, v91
	v_add_f32_e32 v94, 1.0, v94
	v_add_f32_e32 v95, 1.0, v95
	v_rcp_f32_e32 v94, v94
	v_rcp_f32_e32 v95, v95
	s_nop 0
	v_pk_mul_f32 v[92:93], v[92:93], v[94:95]
	s_nop 0
	v_pk_mul_f32 v[92:93], v[92:93], v[96:97]
	s_nop 0
	v_cvt_pk_bf16_f32 v91, v92, v93
	v_mul_f32_e32 v92, 0xbfb8aa3b, v82
	v_mul_f32_e32 v93, 0xbfb8aa3b, v83
	v_exp_f32_e32 v92, v92
	v_exp_f32_e32 v93, v93
	v_add_f32_e32 v92, 1.0, v92
	v_add_f32_e32 v93, 1.0, v93
	v_rcp_f32_e32 v92, v92
	v_rcp_f32_e32 v93, v93
	s_nop 0
	v_pk_mul_f32 v[82:83], v[82:83], v[92:93]
	s_nop 0
	v_pk_mul_f32 v[82:83], v[82:83], v[86:87]
	v_mul_f32_e32 v86, 0xbfb8aa3b, v84
	v_mul_f32_e32 v87, 0xbfb8aa3b, v85
	v_exp_f32_e32 v86, v86
	v_exp_f32_e32 v87, v87
	v_cvt_pk_bf16_f32 v82, v82, v83
	v_add_f32_e32 v86, 1.0, v86
	v_add_f32_e32 v87, 1.0, v87
	v_rcp_f32_e32 v86, v86
	v_rcp_f32_e32 v87, v87
	s_nop 0
	v_pk_mul_f32 v[84:85], v[84:85], v[86:87]
	s_nop 0
	v_pk_mul_f32 v[84:85], v[84:85], v[88:89]
	s_nop 0
	v_cvt_pk_bf16_f32 v83, v84, v85
	v_mul_f32_e32 v84, 0xbfb8aa3b, v74
	v_mul_f32_e32 v85, 0xbfb8aa3b, v75
	v_exp_f32_e32 v84, v84
	v_exp_f32_e32 v85, v85
	v_add_f32_e32 v84, 1.0, v84
	v_add_f32_e32 v85, 1.0, v85
	v_rcp_f32_e32 v84, v84
	v_rcp_f32_e32 v85, v85
	s_nop 0
	v_pk_mul_f32 v[74:75], v[74:75], v[84:85]
	s_nop 0
	v_pk_mul_f32 v[74:75], v[74:75], v[78:79]
	v_mul_f32_e32 v78, 0xbfb8aa3b, v76
	v_mul_f32_e32 v79, 0xbfb8aa3b, v77
	v_exp_f32_e32 v78, v78
	v_exp_f32_e32 v79, v79
	v_cvt_pk_bf16_f32 v74, v74, v75
; DI unsigned pack2(float a, float b) { f2_t v = {a, b}; bf2_t r = __builtin_convertvector(v, bf2_t); return __builtin_bit_cast(unsigned, r); }
; DI float sigmoidf_(float x) { return frcp(1.f + fexp2(-1.44269504089f * x)); }
; DI float siluf_(float x) { return x * sigmoidf_(x); }
; template <class Epi>
; DI void apply_epi_staged(WVP char* smem, AccT& acc, int bc0, const Epi& epi) {
;     ...
;   for (int bj = 0; bj < 2; ++bj) for (int m = 0; m < 4; ++m) {
;     for (int n = 0; n < 2; ++n) {
;       const int rl = wr2 * 64 + m * 16 + fq2 * 4, tc = bj * HALF + wc2 * 32 + n * 16 + fr2;
;       f32x4 r0, r1;
;       epi.tr(acc[0][bj][m][n], acc[1][bj][m][n], rl, bc0 + tc, bj * 8 + m * 2 + n, t2, r0, r1);
;       uint2 v0; v0.x = pack2(r0[0], r0[1]); v0.y = pack2(r0[2], r0[3]);
;       *(uint2*)(smem + tc * PITCH + rl * 2) = v0;
;       if (NC == 256) { uint2 v1; v1.x = pack2(r1[0], r1[1]); v1.y = pack2(r1[2], r1[3]); *(uint2*)(smem + tc * PITCH + (HALF + rl) * 2) = v1; }
;   DI void tr(const f32x4& a0, const f32x4& a1, int, int, int, int, f32x4& r0, f32x4& r1) const {
;     for (int j = 0; j < 4; ++j) r0[j] = ACT == 0 ? siluf_(a0[j]) * a1[j] : a0[j] * sigmoidf_(a1[j]);
;     r1 = r0; }
	v_add_f32_e32 v78, 1.0, v78
	v_add_f32_e32 v79, 1.0, v79
	v_rcp_f32_e32 v78, v78
	v_rcp_f32_e32 v79, v79
	s_nop 0
	v_pk_mul_f32 v[76:77], v[76:77], v[78:79]
	s_nop 0
	v_pk_mul_f32 v[76:77], v[76:77], v[80:81]
	s_nop 0
	v_cvt_pk_bf16_f32 v75, v76, v77
	ds_write2_b64 v122, v[90:91], v[74:75] offset0:8 offset1:12
	v_mul_f32_e32 v74, 0xbfb8aa3b, v66
	v_mul_f32_e32 v75, 0xbfb8aa3b, v67
	v_exp_f32_e32 v74, v74
	v_exp_f32_e32 v75, v75
	v_add_f32_e32 v74, 1.0, v74
	v_add_f32_e32 v75, 1.0, v75
	v_rcp_f32_e32 v74, v74
	v_rcp_f32_e32 v75, v75
	s_nop 0
	v_pk_mul_f32 v[66:67], v[66:67], v[74:75]
	s_nop 0
	v_pk_mul_f32 v[66:67], v[66:67], v[70:71]
	v_mul_f32_e32 v70, 0xbfb8aa3b, v68
	v_mul_f32_e32 v71, 0xbfb8aa3b, v69
	v_exp_f32_e32 v70, v70
	v_exp_f32_e32 v71, v71
	v_cvt_pk_bf16_f32 v66, v66, v67
	v_add_f32_e32 v70, 1.0, v70
	v_add_f32_e32 v71, 1.0, v71
	v_rcp_f32_e32 v70, v70
	v_rcp_f32_e32 v71, v71
	s_nop 0
	v_pk_mul_f32 v[68:69], v[68:69], v[70:71]
	s_nop 0
	v_pk_mul_f32 v[68:69], v[68:69], v[72:73]
	s_nop 0
	v_cvt_pk_bf16_f32 v67, v68, v69
	ds_write2_b64 v100, v[82:83], v[66:67] offset0:40 offset1:44
	v_mul_f32_e32 v66, 0xbfb8aa3b, v58
	v_mul_f32_e32 v67, 0xbfb8aa3b, v59
	v_exp_f32_e32 v66, v66
	v_exp_f32_e32 v67, v67
	v_add_f32_e32 v66, 1.0, v66
	v_add_f32_e32 v67, 1.0, v67
	v_rcp_f32_e32 v66, v66
	v_rcp_f32_e32 v67, v67
	s_nop 0
	v_pk_mul_f32 v[58:59], v[58:59], v[66:67]
	s_nop 0
	v_pk_mul_f32 v[58:59], v[58:59], v[62:63]
	v_mul_f32_e32 v62, 0xbfb8aa3b, v60
	v_mul_f32_e32 v63, 0xbfb8aa3b, v61
	v_exp_f32_e32 v62, v62
	v_exp_f32_e32 v63, v63
	v_cvt_pk_bf16_f32 v58, v58, v59
	v_add_f32_e32 v62, 1.0, v62
	v_add_f32_e32 v63, 1.0, v63
	v_rcp_f32_e32 v62, v62
	v_rcp_f32_e32 v63, v63
	s_nop 0
	v_pk_mul_f32 v[60:61], v[60:61], v[62:63]
	s_nop 0
	v_pk_mul_f32 v[60:61], v[60:61], v[64:65]
	s_nop 0
	v_cvt_pk_bf16_f32 v59, v60, v61
	v_mul_f32_e32 v60, 0xbfb8aa3b, v50
	v_mul_f32_e32 v61, 0xbfb8aa3b, v51
	v_exp_f32_e32 v60, v60
	v_exp_f32_e32 v61, v61
	v_add_f32_e32 v60, 1.0, v60
	v_add_f32_e32 v61, 1.0, v61
	v_rcp_f32_e32 v60, v60
	v_rcp_f32_e32 v61, v61
	s_nop 0
	v_pk_mul_f32 v[50:51], v[50:51], v[60:61]
	s_nop 0
	v_pk_mul_f32 v[50:51], v[50:51], v[54:55]
	v_mul_f32_e32 v54, 0xbfb8aa3b, v52
	v_mul_f32_e32 v55, 0xbfb8aa3b, v53
	v_exp_f32_e32 v54, v54
	v_exp_f32_e32 v55, v55
	v_cvt_pk_bf16_f32 v50, v50, v51
	v_add_f32_e32 v54, 1.0, v54
	v_add_f32_e32 v55, 1.0, v55
	v_rcp_f32_e32 v54, v54
	v_rcp_f32_e32 v55, v55
	s_nop 0
	v_pk_mul_f32 v[52:53], v[52:53], v[54:55]
	s_nop 0
	v_pk_mul_f32 v[52:53], v[52:53], v[56:57]
	s_nop 0
	v_cvt_pk_bf16_f32 v51, v52, v53
	v_mul_f32_e32 v52, 0xbfb8aa3b, v42
	v_mul_f32_e32 v53, 0xbfb8aa3b, v43
	v_exp_f32_e32 v52, v52
	v_exp_f32_e32 v53, v53
	v_add_f32_e32 v52, 1.0, v52
	v_add_f32_e32 v53, 1.0, v53
	v_rcp_f32_e32 v52, v52
	v_rcp_f32_e32 v53, v53
	s_nop 0
	v_pk_mul_f32 v[42:43], v[42:43], v[52:53]
	s_nop 0
	v_pk_mul_f32 v[42:43], v[42:43], v[46:47]
	v_mul_f32_e32 v46, 0xbfb8aa3b, v44
	v_mul_f32_e32 v47, 0xbfb8aa3b, v45
	v_exp_f32_e32 v46, v46
	v_exp_f32_e32 v47, v47
	v_cvt_pk_bf16_f32 v42, v42, v43
	v_add_f32_e32 v46, 1.0, v46
	v_add_f32_e32 v47, 1.0, v47
	v_rcp_f32_e32 v46, v46
	v_rcp_f32_e32 v47, v47
	s_nop 0
	v_pk_mul_f32 v[44:45], v[44:45], v[46:47]
	s_nop 0
	v_pk_mul_f32 v[44:45], v[44:45], v[48:49]
	s_nop 0
	v_cvt_pk_bf16_f32 v43, v44, v45
	v_add_u32_e32 v44, 0x8800, v122
	ds_write2_b64 v44, v[58:59], v[42:43] offset1:4
	v_mul_f32_e32 v42, 0xbfb8aa3b, v34
	v_mul_f32_e32 v43, 0xbfb8aa3b, v35
	v_exp_f32_e32 v42, v42
	v_exp_f32_e32 v43, v43
	v_add_f32_e32 v42, 1.0, v42
	v_add_f32_e32 v43, 1.0, v43
	v_rcp_f32_e32 v42, v42
	v_rcp_f32_e32 v43, v43
	s_nop 0
	v_pk_mul_f32 v[34:35], v[34:35], v[42:43]
	s_nop 0
	v_pk_mul_f32 v[34:35], v[34:35], v[38:39]
	v_mul_f32_e32 v38, 0xbfb8aa3b, v36
	v_mul_f32_e32 v39, 0xbfb8aa3b, v37
	v_exp_f32_e32 v38, v38
	v_exp_f32_e32 v39, v39
	v_cvt_pk_bf16_f32 v34, v34, v35
	v_add_f32_e32 v38, 1.0, v38
	v_add_f32_e32 v39, 1.0, v39
	v_rcp_f32_e32 v38, v38
	v_rcp_f32_e32 v39, v39
	s_nop 0
	v_pk_mul_f32 v[36:37], v[36:37], v[38:39]
	s_nop 0
	v_pk_mul_f32 v[36:37], v[36:37], v[40:41]
	s_nop 0
	v_cvt_pk_bf16_f32 v35, v36, v37
	v_add_u32_e32 v36, 0x9800, v122
	ds_write2_b64 v36, v[50:51], v[34:35] offset0:32 offset1:36
	v_mul_f32_e32 v34, 0xbfb8aa3b, v26
	v_mul_f32_e32 v35, 0xbfb8aa3b, v27
	v_exp_f32_e32 v34, v34
	v_exp_f32_e32 v35, v35
; DI unsigned pack2(float a, float b) { f2_t v = {a, b}; bf2_t r = __builtin_convertvector(v, bf2_t); return __builtin_bit_cast(unsigned, r); }
; template <class Epi>
; DI void apply_epi_staged(WVP char* smem, AccT& acc, int bc0, const Epi& epi) {
;     ...
;   for (int bj = 0; bj < 2; ++bj) for (int m = 0; m < 4; ++m) {
;     for (int n = 0; n < 2; ++n) {
;       const int rl = wr2 * 64 + m * 16 + fq2 * 4, tc = bj * HALF + wc2 * 32 + n * 16 + fr2;
;       f32x4 r0, r1;
;       epi.tr(acc[0][bj][m][n], acc[1][bj][m][n], rl, bc0 + tc, bj * 8 + m * 2 + n, t2, r0, r1);
;       uint2 v0; v0.x = pack2(r0[0], r0[1]); v0.y = pack2(r0[2], r0[3]);
;       *(uint2*)(smem + tc * PITCH + rl * 2) = v0;
;       if (NC == 256) { uint2 v1; v1.x = pack2(r1[0], r1[1]); v1.y = pack2(r1[2], r1[3]); *(uint2*)(smem + tc * PITCH + (HALF + rl) * 2) = v1; }
;     }
;     if (m & 1) __builtin_amdgcn_sched_barrier(0);
;   }
;   __syncthreads();
;   constexpr int CPR = NC / 8;
; #pragma unroll
;   for (int i = 0; i < 256 * CPR / NTHR; ++i) {
;     const int L = i * NTHR + t2, row = L / CPR, ch = L % CPR;
;     const u32x4 v = *(const u32x4*)(smem + row * PITCH + ch * 16);
;     *(u32x4*)(epi.out(bc0 + row, ch)) = v;
;   }
	v_add_f32_e32 v34, 1.0, v34
	v_add_f32_e32 v35, 1.0, v35
	v_rcp_f32_e32 v34, v34
	v_rcp_f32_e32 v35, v35
	s_nop 0
	v_pk_mul_f32 v[26:27], v[26:27], v[34:35]
	s_nop 0
	v_pk_mul_f32 v[26:27], v[26:27], v[30:31]
	v_mul_f32_e32 v30, 0xbfb8aa3b, v28
	v_mul_f32_e32 v31, 0xbfb8aa3b, v29
	v_exp_f32_e32 v30, v30
	v_exp_f32_e32 v31, v31
	v_cvt_pk_bf16_f32 v26, v26, v27
	v_add_f32_e32 v30, 1.0, v30
	v_add_f32_e32 v31, 1.0, v31
	v_rcp_f32_e32 v30, v30
	v_rcp_f32_e32 v31, v31
	s_nop 0
	v_pk_mul_f32 v[28:29], v[28:29], v[30:31]
	s_nop 0
	v_pk_mul_f32 v[28:29], v[28:29], v[32:33]
	s_nop 0
	v_cvt_pk_bf16_f32 v27, v28, v29
	v_mul_f32_e32 v28, 0xbfb8aa3b, v18
	v_mul_f32_e32 v29, 0xbfb8aa3b, v19
	v_exp_f32_e32 v28, v28
	v_exp_f32_e32 v29, v29
	v_add_f32_e32 v28, 1.0, v28
	v_add_f32_e32 v29, 1.0, v29
	v_rcp_f32_e32 v28, v28
	v_rcp_f32_e32 v29, v29
	s_nop 0
	v_pk_mul_f32 v[18:19], v[18:19], v[28:29]
	s_nop 0
	v_pk_mul_f32 v[18:19], v[18:19], v[22:23]
	v_mul_f32_e32 v22, 0xbfb8aa3b, v20
	v_mul_f32_e32 v23, 0xbfb8aa3b, v21
	v_exp_f32_e32 v22, v22
	v_exp_f32_e32 v23, v23
	v_cvt_pk_bf16_f32 v18, v18, v19
	v_add_f32_e32 v22, 1.0, v22
	v_add_f32_e32 v23, 1.0, v23
	v_rcp_f32_e32 v22, v22
	v_rcp_f32_e32 v23, v23
	s_nop 0
	v_pk_mul_f32 v[20:21], v[20:21], v[22:23]
	s_nop 0
	v_pk_mul_f32 v[20:21], v[20:21], v[24:25]
	s_nop 0
	v_cvt_pk_bf16_f32 v19, v20, v21
	v_mul_f32_e32 v20, 0xbfb8aa3b, v10
	v_mul_f32_e32 v21, 0xbfb8aa3b, v11
	v_exp_f32_e32 v20, v20
	v_exp_f32_e32 v21, v21
	v_add_f32_e32 v20, 1.0, v20
	v_add_f32_e32 v21, 1.0, v21
	v_rcp_f32_e32 v20, v20
	v_rcp_f32_e32 v21, v21
	s_nop 0
	v_pk_mul_f32 v[10:11], v[10:11], v[20:21]
	s_nop 0
	v_pk_mul_f32 v[10:11], v[10:11], v[14:15]
	v_mul_f32_e32 v14, 0xbfb8aa3b, v12
	v_mul_f32_e32 v15, 0xbfb8aa3b, v13
	v_exp_f32_e32 v14, v14
	v_exp_f32_e32 v15, v15
	v_cvt_pk_bf16_f32 v10, v10, v11
	v_add_f32_e32 v14, 1.0, v14
	v_add_f32_e32 v15, 1.0, v15
	v_rcp_f32_e32 v14, v14
	v_rcp_f32_e32 v15, v15
	s_nop 0
	v_pk_mul_f32 v[12:13], v[12:13], v[14:15]
	s_nop 0
	v_pk_mul_f32 v[12:13], v[12:13], v[16:17]
	s_nop 0
	v_cvt_pk_bf16_f32 v11, v12, v13
	ds_write2_b64 v44, v[26:27], v[10:11] offset0:8 offset1:12
	v_mul_f32_e32 v10, 0xbfb8aa3b, v2
	v_mul_f32_e32 v11, 0xbfb8aa3b, v3
	v_exp_f32_e32 v10, v10
	v_exp_f32_e32 v11, v11
	v_add_f32_e32 v10, 1.0, v10
	v_add_f32_e32 v11, 1.0, v11
	v_rcp_f32_e32 v10, v10
	v_rcp_f32_e32 v11, v11
	s_nop 0
	v_pk_mul_f32 v[2:3], v[2:3], v[10:11]
	s_nop 0
	v_pk_mul_f32 v[2:3], v[2:3], v[6:7]
	v_mul_f32_e32 v6, 0xbfb8aa3b, v4
	v_mul_f32_e32 v7, 0xbfb8aa3b, v5
	v_exp_f32_e32 v6, v6
	v_exp_f32_e32 v7, v7
	v_cvt_pk_bf16_f32 v2, v2, v3
	v_add_f32_e32 v6, 1.0, v6
	v_add_f32_e32 v7, 1.0, v7
	v_rcp_f32_e32 v6, v6
	v_rcp_f32_e32 v7, v7
	s_nop 0
	v_pk_mul_f32 v[4:5], v[4:5], v[6:7]
	s_nop 0
	v_pk_mul_f32 v[4:5], v[4:5], v[8:9]
	s_nop 0
	v_cvt_pk_bf16_f32 v3, v4, v5
	ds_write2_b64 v36, v[18:19], v[2:3] offset0:40 offset1:44
	s_nop 1
	v_lshrrev_b32_e32 v2, 4, v0
	v_and_b32_e32 v4, 15, v0
	s_movk_i32 s9, 0x110
	v_mul_lo_u32 v3, v2, s9
	v_lshlrev_b32_e32 v4, 4, v4
	v_add_u32_e32 v5, s8, v2
	v_add_u32_e32 v3, v3, v4
	v_mul_lo_u32 v5, v5, s5
	s_lshl_b64 s[10:11], s[10:11], 1
	v_add_u32_e32 v5, v5, v4
	s_add_u32 s0, s54, s10
	s_addc_u32 s1, s55, s11
	s_waitcnt vmcnt(0) lgkmcnt(0)
	s_barrier
	ds_read_b128 v[12:15], v3
	ds_read_b128 v[16:19], v3 offset:8704
	ds_read_b128 v[20:23], v3 offset:17408
	ds_read_b128 v[24:27], v3 offset:26112
	ds_read_b128 v[28:31], v3 offset:34816
	ds_read_b128 v[32:35], v3 offset:43520
	ds_read_b128 v[36:39], v3 offset:52224
	ds_read_b128 v[40:43], v3 offset:60928
	s_waitcnt lgkmcnt(7)
	global_store_dwordx4 v5, v[12:15], s[0:1]
	v_add_u32_e32 v5, 0x2c000, v5
	s_waitcnt lgkmcnt(6)
	global_store_dwordx4 v5, v[16:19], s[0:1]
	v_add_u32_e32 v5, 0x2c000, v5
	s_waitcnt lgkmcnt(5)
	global_store_dwordx4 v5, v[20:23], s[0:1]
	v_add_u32_e32 v5, 0x2c000, v5
	s_waitcnt lgkmcnt(4)
	global_store_dwordx4 v5, v[24:27], s[0:1]
	v_add_u32_e32 v5, 0x2c000, v5
	s_waitcnt lgkmcnt(3)
	global_store_dwordx4 v5, v[28:31], s[0:1]
	v_add_u32_e32 v5, 0x2c000, v5
	s_waitcnt lgkmcnt(2)
	global_store_dwordx4 v5, v[32:35], s[0:1]
	v_add_u32_e32 v5, 0x2c000, v5
	s_waitcnt lgkmcnt(1)
	global_store_dwordx4 v5, v[36:39], s[0:1]
	v_add_u32_e32 v5, 0x2c000, v5
	s_waitcnt lgkmcnt(0)
	global_store_dwordx4 v5, v[40:43], s[0:1]
	v_readlane_b32 s0, v255, 21
	s_nop 0
	s_add_i32 s4, s4, s0

; DI unsigned pack2(float a, float b) { f2_t v = {a, b}; bf2_t r = __builtin_convertvector(v, bf2_t); return __builtin_bit_cast(unsigned, r); }
; template <class Epi>
; DI void apply_epi_staged(WVP char* smem, AccT& acc, int bc0, const Epi& epi) {
;     ...
;   for (int bj = 0; bj < 2; ++bj) for (int m = 0; m < 4; ++m) {
;     for (int n = 0; n < 2; ++n) {
;       const int rl = wr2 * 64 + m * 16 + fq2 * 4, tc = bj * HALF + wc2 * 32 + n * 16 + fr2;
;       f32x4 r0, r1;
;       epi.tr(acc[0][bj][m][n], acc[1][bj][m][n], rl, bc0 + tc, bj * 8 + m * 2 + n, t2, r0, r1);
;       uint2 v0; v0.x = pack2(r0[0], r0[1]); v0.y = pack2(r0[2], r0[3]);
;       *(uint2*)(smem + tc * PITCH + rl * 2) = v0;
;       if (NC == 256) { uint2 v1; v1.x = pack2(r1[0], r1[1]); v1.y = pack2(r1[2], r1[3]); *(uint2*)(smem + tc * PITCH + (HALF + rl) * 2) = v1; }
;     }
;     if (m & 1) __builtin_amdgcn_sched_barrier(0);
;   }
;   __syncthreads();
;   constexpr int CPR = NC / 8;
; #pragma unroll
;   for (int i = 0; i < 256 * CPR / NTHR; ++i) {
;     const int L = i * NTHR + t2, row = L / CPR, ch = L % CPR;
;     const u32x4 v = *(const u32x4*)(smem + row * PITCH + ch * 16);
;     *(u32x4*)(epi.out(bc0 + row, ch)) = v;
;   }
.LBB0_423:
	v_mbcnt_lo_u32_b32 v0, -1, 0
	v_mbcnt_hi_u32_b32 v0, -1, v0
	s_movk_i32 s4, 0x210
	v_add_u32_e32 v130, s3, v0
	v_cvt_pk_bf16_f32 v98, v98, v99
	v_readfirstlane_b32 s0, v130
	s_ashr_i32 s0, s0, 1
	s_and_b32 s1, s0, 0x60
	v_and_or_b32 v131, v0, 15, s1
	v_lshrrev_b32_e32 v0, 1, v0
	s_and_b32 s0, s0, 0xffffff80
	v_and_or_b32 v0, v0, 24, s0
	v_mad_u32_u24 v131, v131, s4, 0
	v_add_u32_e32 v132, v131, v0
	v_cvt_pk_bf16_f32 v99, v100, v101
	v_cvt_pk_bf16_f32 v90, v90, v91
	v_cvt_pk_bf16_f32 v91, v92, v93
	v_cvt_pk_bf16_f32 v82, v82, v83
	v_cvt_pk_bf16_f32 v83, v84, v85
	v_cvt_pk_bf16_f32 v74, v74, v75
	v_cvt_pk_bf16_f32 v75, v76, v77
	v_add_u32_e32 v76, 0x2000, v132
	v_cvt_pk_bf16_f32 v100, v126, v127
	v_cvt_pk_bf16_f32 v101, v128, v129
	v_cvt_pk_bf16_f32 v92, v122, v123
	v_cvt_pk_bf16_f32 v93, v124, v125
	ds_write2_b64 v132, v[98:99], v[82:83] offset1:4
	v_cvt_pk_bf16_f32 v82, v118, v119
	v_cvt_pk_bf16_f32 v83, v120, v121
	ds_write2_b64 v76, v[90:91], v[74:75] offset0:32 offset1:36
	v_cvt_pk_bf16_f32 v74, v114, v115
	v_cvt_pk_bf16_f32 v75, v116, v117
	v_or_b32_e32 v122, 32, v0
	ds_write2_b64 v132, v[100:101], v[82:83] offset0:32 offset1:36
	ds_write2_b64 v76, v[92:93], v[74:75] offset0:64 offset1:68
	v_cvt_pk_bf16_f32 v66, v66, v67
	v_cvt_pk_bf16_f32 v67, v68, v69
	v_cvt_pk_bf16_f32 v58, v58, v59
	v_cvt_pk_bf16_f32 v59, v60, v61
	v_cvt_pk_bf16_f32 v50, v50, v51
	v_cvt_pk_bf16_f32 v51, v52, v53
	v_cvt_pk_bf16_f32 v38, v38, v39
	v_cvt_pk_bf16_f32 v39, v40, v41
	v_cvt_pk_bf16_f32 v68, v110, v111
	v_cvt_pk_bf16_f32 v69, v112, v113
	v_cvt_pk_bf16_f32 v60, v106, v107
	v_cvt_pk_bf16_f32 v61, v108, v109
	ds_write2_b64 v132, v[66:67], v[50:51] offset0:8 offset1:12
	v_cvt_pk_bf16_f32 v50, v102, v103
	v_cvt_pk_bf16_f32 v51, v104, v105
	ds_write2_b64 v76, v[58:59], v[38:39] offset0:40 offset1:44
	v_cvt_pk_bf16_f32 v38, v94, v95
	v_cvt_pk_bf16_f32 v39, v96, v97
	v_or_b32_e32 v74, 64, v0
	v_or_b32_e32 v75, 0x60, v0
	ds_write2_b64 v132, v[68:69], v[50:51] offset0:40 offset1:44
	ds_write2_b64 v76, v[60:61], v[38:39] offset0:72 offset1:76
	v_cvt_pk_bf16_f32 v38, v46, v47
	v_add_u32_e32 v46, 0x10800, v131
	v_cvt_pk_bf16_f32 v39, v48, v49
	v_add_u32_e32 v47, v46, v0
	v_cvt_pk_bf16_f32 v40, v86, v87
	v_cvt_pk_bf16_f32 v41, v88, v89
	ds_write2_b64 v47, v[38:39], v[40:41] offset1:32
	v_add_u32_e32 v38, 0x12900, v131
	v_cvt_pk_bf16_f32 v30, v30, v31
	v_cvt_pk_bf16_f32 v31, v32, v33
	v_add_u32_e32 v0, v38, v0
	v_cvt_pk_bf16_f32 v32, v78, v79
	v_cvt_pk_bf16_f32 v33, v80, v81
	ds_write2_b64 v0, v[30:31], v[32:33] offset1:32
	v_cvt_pk_bf16_f32 v22, v22, v23
	v_cvt_pk_bf16_f32 v23, v24, v25
	v_add_u32_e32 v0, v46, v122
	v_cvt_pk_bf16_f32 v24, v70, v71
	v_cvt_pk_bf16_f32 v25, v72, v73
	ds_write2_b64 v0, v[22:23], v[24:25] offset1:32
	v_cvt_pk_bf16_f32 v18, v18, v19
	v_cvt_pk_bf16_f32 v19, v20, v21
	v_add_u32_e32 v0, v38, v122
	v_cvt_pk_bf16_f32 v20, v62, v63
	v_cvt_pk_bf16_f32 v21, v64, v65
	ds_write2_b64 v0, v[18:19], v[20:21] offset1:32
	v_cvt_pk_bf16_f32 v14, v14, v15
	v_cvt_pk_bf16_f32 v15, v16, v17
	v_add_u32_e32 v0, v46, v74
	v_cvt_pk_bf16_f32 v16, v54, v55
	v_cvt_pk_bf16_f32 v17, v56, v57
	ds_write2_b64 v0, v[14:15], v[16:17] offset1:32
	v_cvt_pk_bf16_f32 v10, v10, v11
	v_cvt_pk_bf16_f32 v11, v12, v13
	v_add_u32_e32 v0, v38, v74
	v_cvt_pk_bf16_f32 v12, v42, v43
	v_cvt_pk_bf16_f32 v13, v44, v45
	ds_write2_b64 v0, v[10:11], v[12:13] offset1:32
	v_cvt_pk_bf16_f32 v6, v6, v7
	v_cvt_pk_bf16_f32 v7, v8, v9
	v_add_u32_e32 v0, v46, v75
	v_cvt_pk_bf16_f32 v8, v34, v35
	v_cvt_pk_bf16_f32 v9, v36, v37
	ds_write2_b64 v0, v[6:7], v[8:9] offset1:32
	v_cvt_pk_bf16_f32 v2, v2, v3
	v_cvt_pk_bf16_f32 v3, v4, v5
	v_add_u32_e32 v0, v38, v75
	v_cvt_pk_bf16_f32 v4, v26, v27
	v_cvt_pk_bf16_f32 v5, v28, v29
	ds_write2_b64 v0, v[2:3], v[4:5] offset1:32
	s_nop 1
	v_lshrrev_b32_e32 v2, 5, v130
	v_and_b32_e32 v0, 31, v130
	v_mul_lo_u32 v3, v2, s4
	v_lshlrev_b32_e32 v4, 4, v0
	v_add_u32_e32 v5, s10, v2
	v_add_u32_e32 v3, v3, v4
	v_mul_lo_u32 v5, v5, s86
	v_lshl_add_u32 v6, v0, 3, s8
	v_add_u32_e32 v7, 0x10800, v3
	v_lshl_add_u32 v5, v6, 1, v5
	v_mov_b32_e32 v252, v205
	v_mov_b32_e32 v253, 0x80
	s_waitcnt vmcnt(0) lgkmcnt(0)
	s_barrier
	ds_read_b128 v[12:15], v3
	ds_read_b128 v[16:19], v3 offset:8448
	ds_read_b128 v[20:23], v3 offset:16896
	ds_read_b128 v[24:27], v3 offset:25344
	ds_read_b128 v[28:31], v3 offset:33792
	ds_read_b128 v[32:35], v3 offset:42240
	ds_read_b128 v[36:39], v3 offset:50688
	ds_read_b128 v[40:43], v3 offset:59136
	ds_read_b128 v[44:47], v7
	ds_read_b128 v[48:51], v7 offset:8448
	ds_read_b128 v[52:55], v7 offset:16896
	ds_read_b128 v[56:59], v7 offset:25344
	ds_read_b128 v[60:63], v7 offset:33792
	ds_read_b128 v[64:67], v7 offset:42240
	ds_read_b128 v[68:71], v7 offset:50688
	ds_read_b128 v[72:75], v7 offset:59136
	v_readlane_b32 s0, v255, 21
	s_waitcnt lgkmcnt(15)
	global_store_dwordx4 v5, v[12:15], s[54:55]
	v_add_u32_e32 v5, 0x26000, v5
	s_waitcnt lgkmcnt(14)
	global_store_dwordx4 v5, v[16:19], s[54:55]
	v_add_u32_e32 v5, 0x26000, v5
	s_waitcnt lgkmcnt(13)
	global_store_dwordx4 v5, v[20:23], s[54:55]
	v_add_u32_e32 v5, 0x26000, v5
	s_waitcnt lgkmcnt(12)
	global_store_dwordx4 v5, v[24:27], s[54:55]
	v_add_u32_e32 v5, 0x26000, v5
	s_waitcnt lgkmcnt(11)
	global_store_dwordx4 v5, v[28:31], s[54:55]
	v_add_u32_e32 v5, 0x26000, v5
	s_waitcnt lgkmcnt(10)
	global_store_dwordx4 v5, v[32:35], s[54:55]
	v_add_u32_e32 v5, 0x26000, v5
	s_waitcnt lgkmcnt(9)
	global_store_dwordx4 v5, v[36:39], s[54:55]
	v_add_u32_e32 v5, 0x26000, v5
	s_waitcnt lgkmcnt(8)
	global_store_dwordx4 v5, v[40:43], s[54:55]
	v_add_u32_e32 v5, 0x26000, v5
	s_waitcnt lgkmcnt(7)
	global_store_dwordx4 v5, v[44:47], s[54:55]
	v_add_u32_e32 v5, 0x26000, v5
	s_waitcnt lgkmcnt(6)
	global_store_dwordx4 v5, v[48:51], s[54:55]
	v_add_u32_e32 v5, 0x26000, v5
	s_waitcnt lgkmcnt(5)
	global_store_dwordx4 v5, v[52:55], s[54:55]
	v_add_u32_e32 v5, 0x26000, v5
	s_waitcnt lgkmcnt(4)
	global_store_dwordx4 v5, v[56:59], s[54:55]
	v_add_u32_e32 v5, 0x26000, v5
	s_waitcnt lgkmcnt(3)
	global_store_dwordx4 v5, v[60:63], s[54:55]
	v_add_u32_e32 v5, 0x26000, v5
	s_waitcnt lgkmcnt(2)
	global_store_dwordx4 v5, v[64:67], s[54:55]
	v_add_u32_e32 v5, 0x26000, v5
	s_waitcnt lgkmcnt(1)
	global_store_dwordx4 v5, v[68:71], s[54:55]
	v_add_u32_e32 v5, 0x26000, v5
	s_waitcnt lgkmcnt(0)
	global_store_dwordx4 v5, v[72:75], s[54:55]
	s_add_i32 s4, s26, s0
	s_cmpk_gt_i32 s4, 0x97f
	s_cbranch_scc1 .LBB0_373
